# grid barrier: non-leader workgroups spin on the cross-XCD generation word directly instead of the per-XCC word their leader bumps afterwards (one release hop removed)
# speedup vs baseline: 1.0005x; 1.0005x over previous
.LBB0_40:
	s_or_b64 exec, exec, s[2:3]
	v_cvt_f32_u32_e32 v5, v2
	s_waitcnt vmcnt(0)
	v_readfirstlane_b32 s2, v4
	v_sub_u32_e32 v4, 0, v2
	v_rcp_iflag_f32_e32 v5, v5
	v_add_u32_e32 v6, s2, v1
	v_mul_f32_e32 v5, 0x4f7ffffe, v5
	v_cvt_u32_f32_e32 v5, v5
	v_mul_lo_u32 v1, v4, v5
	v_mul_hi_u32 v1, v5, v1
	v_add_u32_e32 v1, v5, v1
	v_mul_hi_u32 v1, v6, v1
	v_mul_lo_u32 v4, v1, v2
	v_sub_u32_e32 v4, v6, v4
	v_add_u32_e32 v5, 1, v1
	v_cmp_ge_u32_e32 vcc, v4, v2
	s_nop 1
	v_cndmask_b32_e32 v1, v1, v5, vcc
	v_sub_u32_e32 v5, v4, v2
	v_cndmask_b32_e32 v4, v4, v5, vcc
	v_add_u32_e32 v5, 1, v1
	v_cmp_ge_u32_e32 vcc, v4, v2
	v_add_u32_e32 v4, 1, v6
	s_nop 0
	v_cndmask_b32_e32 v1, v1, v5, vcc
	v_mul_lo_u32 v5, v2, v1
	v_add_u32_e32 v2, v5, v2
	v_cmp_ne_u32_e32 vcc, v4, v2
	s_and_saveexec_b64 s[2:3], vcc
	s_xor_b64 s[2:3], exec, s[2:3]
	s_cbranch_execz .LBB0_54
	v_readlane_b32 s4, v254, 11
	v_readlane_b32 s5, v254, 12
	s_waitcnt lgkmcnt(0)
	s_nop 3
	global_load_dword v0, v3, s[4:5] sc1
	s_waitcnt vmcnt(0)
	v_cmp_eq_u32_e32 vcc, v0, v1
	s_and_saveexec_b64 s[4:5], vcc
	s_cbranch_execz .LBB0_53
	s_mov_b32 s8, 1
	s_mov_b64 s[6:7], 0
	s_branch .LBB0_44

.LBB0_46:
	v_readlane_b32 s12, v254, 11
	v_readlane_b32 s13, v254, 12
	s_add_i32 s8, s8, 1
	s_mov_b64 s[14:15], -1
	s_nop 2
	global_load_dword v0, v3, s[12:13] sc1
	s_waitcnt vmcnt(0)
	v_cmp_ne_u32_e32 vcc, v0, v1
	s_orn2_b64 s[12:13], vcc, exec
	s_branch .LBB0_43
